# rg_scan pass 3 double-buffered: second register set, the 32 loads of the next 8 tokens issued before the current 8 tokens are processed
# speedup vs baseline: 1.0017x; 1.0017x over previous
; __device__ __forceinline__ unsigned cvt_pk_bf16(float lo, float hi) { const f32x2_t v = {lo, hi}; const bf16x2_t b = __builtin_convertvector(v, bf16x2_t); return __builtin_bit_cast(unsigned, b); }
; __device__ __forceinline__ float lo_bf(unsigned w) { return __uint_as_float(w << 16); }
; __device__ __forceinline__ float hi_bf(unsigned w) { return __uint_as_float(w & 0xffff0000u); }
; __device__ void rg_scan_phase(unsigned char* smem, const Params& p) {
;     ...
;         for (int i = 0; i < 128; ++i) { const unsigned l0 = *(const unsigned*)(la0 + (size_t)i * 512), v0 = *(const unsigned*)(u0 + (size_t)i * 512);
;             hfx = __expf(lo_bf(l0)) * hfx + lo_bf(v0); hfy = __expf(hi_bf(l0)) * hfy + hi_bf(v0); *(unsigned*)(hfp + (size_t)i * 512) = cvt_pk_bf16(hfx, hfy); }
.LBB0_179:
	v_lshl_add_u64 v[6:7], v[4:5], 0, s[14:15]
	v_add_co_u32_e64 v18, s[0:1], s31, v6
	v_add_co_u32_e32 v16, vcc, 0x12c00000, v6
	s_nop 0
	v_addc_co_u32_e64 v19, s[0:1], 0, v7, s[0:1]
	v_add_co_u32_e64 v20, s[0:1], s34, v6
	v_addc_co_u32_e32 v17, vcc, 0, v7, vcc
	s_nop 0
	v_addc_co_u32_e64 v21, s[0:1], 0, v7, s[0:1]
	global_load_dword v22, v[18:19], off
	global_load_dword v23, v[20:21], off
	global_load_dword v24, v[18:19], off offset:1024
	global_load_dword v25, v[20:21], off offset:1024
	global_load_dword v26, v[18:19], off offset:2048
	global_load_dword v27, v[20:21], off offset:2048
	global_load_dword v28, v[20:21], off offset:3072
	global_load_dword v29, v[18:19], off offset:3072
	v_add_co_u32_e32 v18, vcc, 0x16c00000, v6
	global_load_dword v30, v[16:17], off
	global_load_dword v31, v[16:17], off offset:1024
	global_load_dword v38, v[16:17], off offset:2048
	v_addc_co_u32_e32 v19, vcc, 0, v7, vcc
	global_load_dword v39, v[18:19], off
	global_load_dword v40, v[18:19], off offset:1024
	global_load_dword v41, v[18:19], off offset:2048
	global_load_dword v42, v[18:19], off offset:3072
	global_load_dword v43, v[16:17], off offset:3072
	s_mov_b32 s16, 0x1ac00000
	v_add_co_u32_e32 v20, vcc, s16, v6
	s_mov_b32 s17, 0x1ac01000
	s_nop 0
	v_addc_co_u32_e32 v21, vcc, 0, v7, vcc
	v_add_co_u32_e32 v6, vcc, s17, v6
	s_add_u32 s14, s14, 0x2000
	s_nop 0
	v_addc_co_u32_e32 v7, vcc, 0, v7, vcc
	s_addc_u32 s15, s15, 0
	s_cmp_eq_u32 s14, 0x20000
	s_waitcnt vmcnt(15)
	v_lshlrev_b32_e32 v44, 16, v22
	s_waitcnt vmcnt(14)
	v_lshlrev_b32_e32 v16, 16, v23
	s_waitcnt vmcnt(13)
	v_lshlrev_b32_e32 v46, 16, v24
	s_waitcnt vmcnt(12)
	v_lshlrev_b32_e32 v18, 16, v25
	v_and_b32_e32 v47, 0xffff0000, v24
	v_and_b32_e32 v19, 0xffff0000, v25
	s_waitcnt vmcnt(11)
	v_lshlrev_b32_e32 v48, 16, v26
	s_waitcnt vmcnt(9)
	v_lshlrev_b32_e32 v24, 16, v28
	v_and_b32_e32 v25, 0xffff0000, v28
	s_waitcnt vmcnt(7)
	v_lshlrev_b32_e32 v28, 16, v30
	v_and_b32_e32 v30, 0xffff0000, v30
	v_and_b32_e32 v45, 0xffff0000, v22
	v_and_b32_e32 v17, 0xffff0000, v23
	v_lshlrev_b32_e32 v22, 16, v27
	v_and_b32_e32 v26, 0xffff0000, v26
	v_and_b32_e32 v23, 0xffff0000, v27
	v_lshlrev_b32_e32 v27, 16, v29
	v_and_b32_e32 v29, 0xffff0000, v29
	s_waitcnt vmcnt(6)
	v_lshlrev_b32_e32 v49, 16, v31
	v_and_b32_e32 v31, 0xffff0000, v31
	v_mul_f32_e32 v44, 0x3fb8aa3b, v44
	v_mul_f32_e32 v48, 0x3fb8aa3b, v48
	v_mul_f32_e32 v54, 0x3fb8aa3b, v28
	v_mul_f32_e32 v55, 0x3fb8aa3b, v30
	s_waitcnt vmcnt(5)
	v_lshlrev_b32_e32 v50, 16, v38
	v_and_b32_e32 v38, 0xffff0000, v38
	v_mul_f32_e32 v45, 0x3fb8aa3b, v45
	v_mul_f32_e32 v51, 0x3fb8aa3b, v26
	v_mul_f32_e32 v53, 0x3fb8aa3b, v29
	v_mul_f32_e32 v56, 0x3fb8aa3b, v49
	s_waitcnt vmcnt(3)
	v_lshlrev_b32_e32 v28, 16, v40
	v_mul_f32_e32 v57, 0x3fb8aa3b, v31
	v_and_b32_e32 v29, 0xffff0000, v40
	v_exp_f32_e32 v40, v44
	v_exp_f32_e32 v44, v48
	v_exp_f32_e32 v48, v54
	v_exp_f32_e32 v49, v55
	v_mul_f32_e32 v46, 0x3fb8aa3b, v46
	v_mul_f32_e32 v47, 0x3fb8aa3b, v47
	v_mul_f32_e32 v52, 0x3fb8aa3b, v27
	v_mul_f32_e32 v58, 0x3fb8aa3b, v50
	s_waitcnt vmcnt(2)
	v_lshlrev_b32_e32 v30, 16, v41
	v_mul_f32_e32 v59, 0x3fb8aa3b, v38
	v_and_b32_e32 v31, 0xffff0000, v41
	s_waitcnt vmcnt(0)
	v_lshlrev_b32_e32 v60, 16, v43
	v_and_b32_e32 v61, 0xffff0000, v43
	v_exp_f32_e32 v41, v45
	v_exp_f32_e32 v45, v51
	v_exp_f32_e32 v50, v56
	v_exp_f32_e32 v51, v57
	v_lshlrev_b32_e32 v26, 16, v39
	v_and_b32_e32 v27, 0xffff0000, v39
	v_lshlrev_b32_e32 v38, 16, v42
	v_and_b32_e32 v39, 0xffff0000, v42
	v_exp_f32_e32 v42, v46
	v_exp_f32_e32 v43, v47
	v_exp_f32_e32 v46, v52
	v_exp_f32_e32 v47, v53
	v_exp_f32_e32 v52, v58
	v_exp_f32_e32 v53, v59
	v_mul_f32_e32 v54, 0x3fb8aa3b, v60
	v_mul_f32_e32 v55, 0x3fb8aa3b, v61
	v_exp_f32_e32 v54, v54
	v_exp_f32_e32 v55, v55
	v_pk_fma_f32 v[2:3], v[2:3], v[48:49], v[26:27]
	s_nop 0
	v_cvt_pk_bf16_f32 v26, v2, v3
	v_pk_fma_f32 v[2:3], v[2:3], v[50:51], v[28:29]
	global_store_dword v[6:7], v26, off offset:-4096
	v_cvt_pk_bf16_f32 v26, v2, v3
	v_pk_fma_f32 v[2:3], v[2:3], v[52:53], v[30:31]
	global_store_dword v[20:21], v26, off offset:1024
	v_cvt_pk_bf16_f32 v26, v2, v3
	v_pk_fma_f32 v[2:3], v[2:3], v[54:55], v[38:39]
	global_store_dword v[20:21], v26, off offset:2048
	v_cvt_pk_bf16_f32 v26, v2, v3
	v_pk_fma_f32 v[2:3], v[2:3], v[40:41], v[16:17]
	global_store_dword v[20:21], v26, off offset:3072
	v_cvt_pk_bf16_f32 v16, v2, v3
	v_pk_fma_f32 v[2:3], v[2:3], v[42:43], v[18:19]
	global_store_dword v[6:7], v16, off
	v_cvt_pk_bf16_f32 v16, v2, v3
	v_pk_fma_f32 v[2:3], v[2:3], v[44:45], v[22:23]
	global_store_dword v[6:7], v16, off offset:1024
	v_cvt_pk_bf16_f32 v16, v2, v3
	v_pk_fma_f32 v[2:3], v[2:3], v[46:47], v[24:25]
	global_store_dword v[6:7], v16, off offset:2048
	v_cvt_pk_bf16_f32 v16, v2, v3
	global_store_dword v[6:7], v16, off offset:3072
	s_cbranch_scc0 .LBB0_179
; __device__ __forceinline__ float lo_bf(unsigned w) { return __uint_as_float(w << 16); }
; __device__ __forceinline__ float hi_bf(unsigned w) { return __uint_as_float(w & 0xffff0000u); }
; __device__ void rg_scan_phase(unsigned char* smem, const Params& p) {
;     ...
;         for (int i = 0; i < 128; ++i) { const int tt = 127 - i; const unsigned l1 = *(const unsigned*)(la1 + (size_t)tt * 512), v1 = *(const unsigned*)(u1 + (size_t)tt * 512);
;             hbx = __expf(lo_bf(l1)) * hbx + lo_bf(v1); hby = __expf(hi_bf(l1)) * hby + hi_bf(v1);
;             const unsigned gw = *(const unsigned*)(gp + (size_t)tt * 1024), hw = *(const unsigned*)(hfp + (size_t)tt * 512);
	v_mov_b32_e32 v2, 0x600000
	v_mad_i64_i32 v[2:3], s[0:1], s12, v2, v[10:11]
	s_lshl_b64 s[0:1], s[12:13], 22
	v_lshlrev_b32_e32 v184, 1, v184
	v_lshl_add_u64 v[4:5], v[12:13], 0, s[0:1]
	s_movk_i32 s36, 0xe000
	v_lshl_add_u64 v[2:3], v[2:3], 0, v[184:185]
	v_lshl_add_u64 v[4:5], v[4:5], 0, v[184:185]
	s_movk_i32 s12, 0x80
	s_mov_b32 s37, -1
	v_lshl_add_u64 v[90:91], s[6:7], 0, v[14:15]
	s_mov_b32 s0, 0x14c1fc00
	s_mov_b32 s1, 0
	v_lshl_add_u64 v[38:39], v[90:91], 0, s[0:1]
	s_mov_b32 s0, 0x18c1fc00
	v_lshl_add_u64 v[56:57], v[90:91], 0, s[0:1]
	s_mov_b32 s0, 0x1ac1fc00
	v_lshl_add_u64 v[58:59], v[90:91], 0, s[0:1]
	v_lshl_add_u64 v[60:61], s[6:7], 0, v[4:5]
	s_mov_b32 s0, 0xdc3fc00
	v_lshl_add_u64 v[60:61], v[60:61], 0, s[0:1]
	s_mov_b32 s14, 0xfffff000
	s_mov_b32 s15, -1
	global_load_dword v16, v[38:39], off
	global_load_dword v17, v[56:57], off
	global_load_dword v18, v[60:61], off
	global_load_dword v19, v[58:59], off
	global_load_dword v20, v[38:39], off offset:-1024
	global_load_dword v21, v[56:57], off offset:-1024
	global_load_dword v22, v[60:61], off offset:-2048
	global_load_dword v23, v[58:59], off offset:-1024
	v_lshl_add_u64 v[60:61], v[60:61], 0, s[14:15]
	global_load_dword v24, v[38:39], off offset:-2048
	global_load_dword v25, v[56:57], off offset:-2048
	global_load_dword v26, v[60:61], off
	global_load_dword v27, v[58:59], off offset:-2048
	global_load_dword v28, v[38:39], off offset:-3072
	global_load_dword v29, v[56:57], off offset:-3072
	global_load_dword v30, v[60:61], off offset:-2048
	global_load_dword v31, v[58:59], off offset:-3072
	v_lshl_add_u64 v[38:39], v[38:39], 0, s[14:15]
	v_lshl_add_u64 v[56:57], v[56:57], 0, s[14:15]
	v_lshl_add_u64 v[58:59], v[58:59], 0, s[14:15]
	v_lshl_add_u64 v[60:61], v[60:61], 0, s[14:15]
	global_load_dword v40, v[38:39], off
	global_load_dword v41, v[56:57], off
	global_load_dword v42, v[60:61], off
	global_load_dword v43, v[58:59], off
	global_load_dword v44, v[38:39], off offset:-1024
	global_load_dword v45, v[56:57], off offset:-1024
	global_load_dword v46, v[60:61], off offset:-2048
	global_load_dword v47, v[58:59], off offset:-1024
	v_lshl_add_u64 v[60:61], v[60:61], 0, s[14:15]
	global_load_dword v48, v[38:39], off offset:-2048
	global_load_dword v49, v[56:57], off offset:-2048
	global_load_dword v50, v[60:61], off
	global_load_dword v51, v[58:59], off offset:-2048
	global_load_dword v52, v[38:39], off offset:-3072
	global_load_dword v53, v[56:57], off offset:-3072
	global_load_dword v54, v[60:61], off offset:-2048
	global_load_dword v55, v[58:59], off offset:-3072
	v_lshl_add_u64 v[14:15], v[14:15], 0, s[36:37]
	s_movk_i32 s14, 0xc000
	v_lshl_add_u64 v[4:5], v[4:5], 0, s[14:15]
.LBB0_181:
	v_lshl_add_u64 v[90:91], s[6:7], 0, v[14:15]
	s_mov_b32 s0, 0x14c1fc00
	s_mov_b32 s1, 0
	v_lshl_add_u64 v[38:39], v[90:91], 0, s[0:1]
	s_mov_b32 s0, 0x18c1fc00
	v_lshl_add_u64 v[56:57], v[90:91], 0, s[0:1]
	s_mov_b32 s0, 0x1ac1fc00
	v_lshl_add_u64 v[58:59], v[90:91], 0, s[0:1]
	v_lshl_add_u64 v[60:61], s[6:7], 0, v[4:5]
	s_mov_b32 s0, 0xdc3fc00
	v_lshl_add_u64 v[60:61], v[60:61], 0, s[0:1]
	s_mov_b32 s14, 0xfffff000
	s_mov_b32 s15, -1
	global_load_dword v96, v[38:39], off
	global_load_dword v97, v[56:57], off
	global_load_dword v98, v[60:61], off
	global_load_dword v99, v[58:59], off
	global_load_dword v100, v[38:39], off offset:-1024
	global_load_dword v101, v[56:57], off offset:-1024
	global_load_dword v102, v[60:61], off offset:-2048
	global_load_dword v103, v[58:59], off offset:-1024
	v_lshl_add_u64 v[60:61], v[60:61], 0, s[14:15]
	global_load_dword v104, v[38:39], off offset:-2048
	global_load_dword v105, v[56:57], off offset:-2048
	global_load_dword v106, v[60:61], off
	global_load_dword v107, v[58:59], off offset:-2048
	global_load_dword v108, v[38:39], off offset:-3072
	global_load_dword v109, v[56:57], off offset:-3072
	global_load_dword v110, v[60:61], off offset:-2048
	global_load_dword v111, v[58:59], off offset:-3072
	v_lshl_add_u64 v[38:39], v[38:39], 0, s[14:15]
	v_lshl_add_u64 v[56:57], v[56:57], 0, s[14:15]
	v_lshl_add_u64 v[58:59], v[58:59], 0, s[14:15]
	v_lshl_add_u64 v[60:61], v[60:61], 0, s[14:15]
	global_load_dword v112, v[38:39], off
	global_load_dword v113, v[56:57], off
	global_load_dword v114, v[60:61], off
	global_load_dword v115, v[58:59], off
	global_load_dword v116, v[38:39], off offset:-1024
	global_load_dword v117, v[56:57], off offset:-1024
	global_load_dword v118, v[60:61], off offset:-2048
	global_load_dword v119, v[58:59], off offset:-1024
	v_lshl_add_u64 v[60:61], v[60:61], 0, s[14:15]
	global_load_dword v120, v[38:39], off offset:-2048
	global_load_dword v121, v[56:57], off offset:-2048
	global_load_dword v122, v[60:61], off
	global_load_dword v123, v[58:59], off offset:-2048
	global_load_dword v124, v[38:39], off offset:-3072
	global_load_dword v125, v[56:57], off offset:-3072
	global_load_dword v126, v[60:61], off offset:-2048
	global_load_dword v127, v[58:59], off offset:-3072
	v_lshl_add_u64 v[14:15], v[14:15], 0, s[36:37]
	s_movk_i32 s14, 0xc000
	v_lshl_add_u64 v[4:5], v[4:5], 0, s[14:15]
	v_lshl_add_u64 v[6:7], s[6:7], 0, v[2:3]
	s_mov_b32 s0, 0x1cc5fc00
	s_mov_b32 s1, 0
	v_lshl_add_u64 v[6:7], v[6:7], 0, s[0:1]
	s_mov_b32 s16, 0xfffff400
	s_mov_b32 s17, -1
	s_waitcnt vmcnt(60)
; __device__ __forceinline__ unsigned cvt_pk_bf16(float lo, float hi) { const f32x2_t v = {lo, hi}; const bf16x2_t b = __builtin_convertvector(v, bf16x2_t); return __builtin_bit_cast(unsigned, b); }
; __device__ __forceinline__ float lo_bf(unsigned w) { return __uint_as_float(w << 16); }
; __device__ __forceinline__ float hi_bf(unsigned w) { return __uint_as_float(w & 0xffff0000u); }
; __device__ __forceinline__ float gelu_tanh_(float gx) { const float inner = 0.7978845608028654f * (gx + 0.044715f * gx * gx * gx); const float th = 1.0f - 2.0f * __builtin_amdgcn_rcpf(1.0f + __expf(2.0f * inner)); return 0.5f * gx * (1.0f + th); }
; __device__ void rg_scan_phase(unsigned char* smem, const Params& p) {
;     ...
;         for (int i = 0; i < 128; ++i) { const int tt = 127 - i; const unsigned l1 = *(const unsigned*)(la1 + (size_t)tt * 512), v1 = *(const unsigned*)(u1 + (size_t)tt * 512);
;             hbx = __expf(lo_bf(l1)) * hbx + lo_bf(v1); hby = __expf(hi_bf(l1)) * hby + hi_bf(v1);
;             const unsigned gw = *(const unsigned*)(gp + (size_t)tt * 1024), hw = *(const unsigned*)(hfp + (size_t)tt * 512);
;             *(unsigned*)(yo + (size_t)tt * 1536) = cvt_pk_bf16((lo_bf(hw) + hbx) * gelu_tanh_(lo_bf(gw)), (hi_bf(hw) + hby) * gelu_tanh_(hi_bf(gw))); }
	v_and_b32_e32 v56, 0xffff0000, v16
	v_lshlrev_b32_e32 v57, 16, v16
	v_mul_f32_e32 v56, 0x3fb8aa3b, v56
	v_mul_f32_e32 v57, 0x3fb8aa3b, v57
	v_exp_f32_e32 v56, v56
	v_exp_f32_e32 v57, v57
	v_and_b32_e32 v58, 0xffff0000, v17
	v_lshlrev_b32_e32 v59, 16, v17
	v_lshlrev_b32_e32 v60, 16, v18
	v_and_b32_e32 v61, 0xffff0000, v18
	v_pk_fma_f32 v[0:1], v[0:1], v[56:57], v[58:59]
	v_mul_f32_e32 v62, 0x3d372713, v60
	v_mul_f32_e32 v63, 0x3d372713, v61
	v_pk_mul_f32 v[38:39], v[60:61], 0.5 op_sel_hi:[1,0]
	v_mul_f32_e32 v62, v62, v60
	v_mul_f32_e32 v63, v63, v61
	v_fma_f32 v62, v62, v60, v60
	v_fma_f32 v63, v63, v61, v61
	v_mul_f32_e32 v62, 0x3f4c422a, v62
	v_mul_f32_e32 v63, 0x3f4c422a, v63
	v_add_f32_e32 v62, v62, v62
	v_add_f32_e32 v63, v63, v63
	v_mul_f32_e32 v62, 0x3fb8aa3b, v62
	v_mul_f32_e32 v63, 0x3fb8aa3b, v63
	v_exp_f32_e32 v62, v62
	v_exp_f32_e32 v63, v63
	v_lshlrev_b32_e32 v60, 16, v19
	v_and_b32_e32 v61, 0xffff0000, v19
	v_add_f32_e32 v62, 1.0, v62
	v_add_f32_e32 v63, 1.0, v63
	v_rcp_f32_e32 v62, v62
	v_rcp_f32_e32 v63, v63
	v_pk_add_f32 v[60:61], v[0:1], v[60:61] op_sel:[1,0] op_sel_hi:[0,1]
	v_pk_fma_f32 v[62:63], v[62:63], 2.0, 1.0 op_sel_hi:[1,0,0] neg_lo:[1,0,0] neg_hi:[1,0,0]
	s_nop 0
	v_pk_add_f32 v[62:63], v[62:63], 1.0 op_sel_hi:[1,0]
	s_nop 0
	v_pk_mul_f32 v[62:63], v[38:39], v[62:63]
	s_nop 0
	v_pk_mul_f32 v[60:61], v[60:61], v[62:63]
	s_nop 0
	v_cvt_pk_bf16_f32 v60, v60, v61
	global_store_dword v[6:7], v60, off
	v_lshl_add_u64 v[6:7], v[6:7], 0, s[16:17]
	s_waitcnt vmcnt(57)
	v_and_b32_e32 v56, 0xffff0000, v20
	v_lshlrev_b32_e32 v57, 16, v20
	v_mul_f32_e32 v56, 0x3fb8aa3b, v56
	v_mul_f32_e32 v57, 0x3fb8aa3b, v57
	v_exp_f32_e32 v56, v56
	v_exp_f32_e32 v57, v57
	v_and_b32_e32 v58, 0xffff0000, v21
	v_lshlrev_b32_e32 v59, 16, v21
	v_lshlrev_b32_e32 v60, 16, v22
	v_and_b32_e32 v61, 0xffff0000, v22
	v_pk_fma_f32 v[0:1], v[0:1], v[56:57], v[58:59]
	v_mul_f32_e32 v62, 0x3d372713, v60
	v_mul_f32_e32 v63, 0x3d372713, v61
	v_pk_mul_f32 v[38:39], v[60:61], 0.5 op_sel_hi:[1,0]
	v_mul_f32_e32 v62, v62, v60
	v_mul_f32_e32 v63, v63, v61
	v_fma_f32 v62, v62, v60, v60
	v_fma_f32 v63, v63, v61, v61
	v_mul_f32_e32 v62, 0x3f4c422a, v62
	v_mul_f32_e32 v63, 0x3f4c422a, v63
	v_add_f32_e32 v62, v62, v62
	v_add_f32_e32 v63, v63, v63
	v_mul_f32_e32 v62, 0x3fb8aa3b, v62
	v_mul_f32_e32 v63, 0x3fb8aa3b, v63
	v_exp_f32_e32 v62, v62
	v_exp_f32_e32 v63, v63
	v_lshlrev_b32_e32 v60, 16, v23
	v_and_b32_e32 v61, 0xffff0000, v23
	v_add_f32_e32 v62, 1.0, v62
	v_add_f32_e32 v63, 1.0, v63
	v_rcp_f32_e32 v62, v62
	v_rcp_f32_e32 v63, v63
	v_pk_add_f32 v[60:61], v[0:1], v[60:61] op_sel:[1,0] op_sel_hi:[0,1]
	v_pk_fma_f32 v[62:63], v[62:63], 2.0, 1.0 op_sel_hi:[1,0,0] neg_lo:[1,0,0] neg_hi:[1,0,0]
	s_nop 0
	v_pk_add_f32 v[62:63], v[62:63], 1.0 op_sel_hi:[1,0]
	s_nop 0
	v_pk_mul_f32 v[62:63], v[38:39], v[62:63]
	s_nop 0
	v_pk_mul_f32 v[60:61], v[60:61], v[62:63]
	s_nop 0
	v_cvt_pk_bf16_f32 v60, v60, v61
	global_store_dword v[6:7], v60, off
	v_lshl_add_u64 v[6:7], v[6:7], 0, s[16:17]
	s_waitcnt vmcnt(54)
	v_and_b32_e32 v56, 0xffff0000, v24
	v_lshlrev_b32_e32 v57, 16, v24
	v_mul_f32_e32 v56, 0x3fb8aa3b, v56
	v_mul_f32_e32 v57, 0x3fb8aa3b, v57
	v_exp_f32_e32 v56, v56
	v_exp_f32_e32 v57, v57
	v_and_b32_e32 v58, 0xffff0000, v25
	v_lshlrev_b32_e32 v59, 16, v25
	v_lshlrev_b32_e32 v60, 16, v26
	v_and_b32_e32 v61, 0xffff0000, v26
	v_pk_fma_f32 v[0:1], v[0:1], v[56:57], v[58:59]
	v_mul_f32_e32 v62, 0x3d372713, v60
	v_mul_f32_e32 v63, 0x3d372713, v61
	v_pk_mul_f32 v[38:39], v[60:61], 0.5 op_sel_hi:[1,0]
	v_mul_f32_e32 v62, v62, v60
	v_mul_f32_e32 v63, v63, v61
	v_fma_f32 v62, v62, v60, v60
	v_fma_f32 v63, v63, v61, v61
	v_mul_f32_e32 v62, 0x3f4c422a, v62
	v_mul_f32_e32 v63, 0x3f4c422a, v63
	v_add_f32_e32 v62, v62, v62
	v_add_f32_e32 v63, v63, v63
	v_mul_f32_e32 v62, 0x3fb8aa3b, v62
	v_mul_f32_e32 v63, 0x3fb8aa3b, v63
	v_exp_f32_e32 v62, v62
	v_exp_f32_e32 v63, v63
	v_lshlrev_b32_e32 v60, 16, v27
	v_and_b32_e32 v61, 0xffff0000, v27
	v_add_f32_e32 v62, 1.0, v62
	v_add_f32_e32 v63, 1.0, v63
	v_rcp_f32_e32 v62, v62
	v_rcp_f32_e32 v63, v63
	v_pk_add_f32 v[60:61], v[0:1], v[60:61] op_sel:[1,0] op_sel_hi:[0,1]
	v_pk_fma_f32 v[62:63], v[62:63], 2.0, 1.0 op_sel_hi:[1,0,0] neg_lo:[1,0,0] neg_hi:[1,0,0]
	s_nop 0
	v_pk_add_f32 v[62:63], v[62:63], 1.0 op_sel_hi:[1,0]
	s_nop 0
	v_pk_mul_f32 v[62:63], v[38:39], v[62:63]
	s_nop 0
	v_pk_mul_f32 v[60:61], v[60:61], v[62:63]
	s_nop 0
	v_cvt_pk_bf16_f32 v60, v60, v61
	global_store_dword v[6:7], v60, off
	v_lshl_add_u64 v[6:7], v[6:7], 0, s[16:17]
	s_waitcnt vmcnt(51)
	v_and_b32_e32 v56, 0xffff0000, v28
	v_lshlrev_b32_e32 v57, 16, v28
	v_mul_f32_e32 v56, 0x3fb8aa3b, v56
	v_mul_f32_e32 v57, 0x3fb8aa3b, v57
	v_exp_f32_e32 v56, v56
	v_exp_f32_e32 v57, v57
	v_and_b32_e32 v58, 0xffff0000, v29
	v_lshlrev_b32_e32 v59, 16, v29
	v_lshlrev_b32_e32 v60, 16, v30
	v_and_b32_e32 v61, 0xffff0000, v30
	v_pk_fma_f32 v[0:1], v[0:1], v[56:57], v[58:59]
	v_mul_f32_e32 v62, 0x3d372713, v60
	v_mul_f32_e32 v63, 0x3d372713, v61
	v_pk_mul_f32 v[38:39], v[60:61], 0.5 op_sel_hi:[1,0]
	v_mul_f32_e32 v62, v62, v60
	v_mul_f32_e32 v63, v63, v61
	v_fma_f32 v62, v62, v60, v60
	v_fma_f32 v63, v63, v61, v61
	v_mul_f32_e32 v62, 0x3f4c422a, v62
	v_mul_f32_e32 v63, 0x3f4c422a, v63
	v_add_f32_e32 v62, v62, v62
	v_add_f32_e32 v63, v63, v63
	v_mul_f32_e32 v62, 0x3fb8aa3b, v62
	v_mul_f32_e32 v63, 0x3fb8aa3b, v63
	v_exp_f32_e32 v62, v62
	v_exp_f32_e32 v63, v63
	v_lshlrev_b32_e32 v60, 16, v31
	v_and_b32_e32 v61, 0xffff0000, v31
	v_add_f32_e32 v62, 1.0, v62
	v_add_f32_e32 v63, 1.0, v63
	v_rcp_f32_e32 v62, v62
	v_rcp_f32_e32 v63, v63
	v_pk_add_f32 v[60:61], v[0:1], v[60:61] op_sel:[1,0] op_sel_hi:[0,1]
	v_pk_fma_f32 v[62:63], v[62:63], 2.0, 1.0 op_sel_hi:[1,0,0] neg_lo:[1,0,0] neg_hi:[1,0,0]
	s_nop 0
	v_pk_add_f32 v[62:63], v[62:63], 1.0 op_sel_hi:[1,0]
	s_nop 0
	v_pk_mul_f32 v[62:63], v[38:39], v[62:63]
	s_nop 0
	v_pk_mul_f32 v[60:61], v[60:61], v[62:63]
	s_nop 0
	v_cvt_pk_bf16_f32 v60, v60, v61
	global_store_dword v[6:7], v60, off
	v_lshl_add_u64 v[6:7], v[6:7], 0, s[16:17]
	s_waitcnt vmcnt(48)
; __device__ __forceinline__ unsigned cvt_pk_bf16(float lo, float hi) { const f32x2_t v = {lo, hi}; const bf16x2_t b = __builtin_convertvector(v, bf16x2_t); return __builtin_bit_cast(unsigned, b); }
; __device__ __forceinline__ float lo_bf(unsigned w) { return __uint_as_float(w << 16); }
; __device__ __forceinline__ float hi_bf(unsigned w) { return __uint_as_float(w & 0xffff0000u); }
; __device__ __forceinline__ float gelu_tanh_(float gx) { const float inner = 0.7978845608028654f * (gx + 0.044715f * gx * gx * gx); const float th = 1.0f - 2.0f * __builtin_amdgcn_rcpf(1.0f + __expf(2.0f * inner)); return 0.5f * gx * (1.0f + th); }
; __device__ void rg_scan_phase(unsigned char* smem, const Params& p) {
;     ...
;         for (int i = 0; i < 128; ++i) { const int tt = 127 - i; const unsigned l1 = *(const unsigned*)(la1 + (size_t)tt * 512), v1 = *(const unsigned*)(u1 + (size_t)tt * 512);
;             hbx = __expf(lo_bf(l1)) * hbx + lo_bf(v1); hby = __expf(hi_bf(l1)) * hby + hi_bf(v1);
;             const unsigned gw = *(const unsigned*)(gp + (size_t)tt * 1024), hw = *(const unsigned*)(hfp + (size_t)tt * 512);
;             *(unsigned*)(yo + (size_t)tt * 1536) = cvt_pk_bf16((lo_bf(hw) + hbx) * gelu_tanh_(lo_bf(gw)), (hi_bf(hw) + hby) * gelu_tanh_(hi_bf(gw))); }
	v_and_b32_e32 v56, 0xffff0000, v40
	v_lshlrev_b32_e32 v57, 16, v40
	v_mul_f32_e32 v56, 0x3fb8aa3b, v56
	v_mul_f32_e32 v57, 0x3fb8aa3b, v57
	v_exp_f32_e32 v56, v56
	v_exp_f32_e32 v57, v57
	v_and_b32_e32 v58, 0xffff0000, v41
	v_lshlrev_b32_e32 v59, 16, v41
	v_lshlrev_b32_e32 v60, 16, v42
	v_and_b32_e32 v61, 0xffff0000, v42
	v_pk_fma_f32 v[0:1], v[0:1], v[56:57], v[58:59]
	v_mul_f32_e32 v62, 0x3d372713, v60
	v_mul_f32_e32 v63, 0x3d372713, v61
	v_pk_mul_f32 v[38:39], v[60:61], 0.5 op_sel_hi:[1,0]
	v_mul_f32_e32 v62, v62, v60
	v_mul_f32_e32 v63, v63, v61
	v_fma_f32 v62, v62, v60, v60
	v_fma_f32 v63, v63, v61, v61
	v_mul_f32_e32 v62, 0x3f4c422a, v62
	v_mul_f32_e32 v63, 0x3f4c422a, v63
	v_add_f32_e32 v62, v62, v62
	v_add_f32_e32 v63, v63, v63
	v_mul_f32_e32 v62, 0x3fb8aa3b, v62
	v_mul_f32_e32 v63, 0x3fb8aa3b, v63
	v_exp_f32_e32 v62, v62
	v_exp_f32_e32 v63, v63
	v_lshlrev_b32_e32 v60, 16, v43
	v_and_b32_e32 v61, 0xffff0000, v43
	v_add_f32_e32 v62, 1.0, v62
	v_add_f32_e32 v63, 1.0, v63
	v_rcp_f32_e32 v62, v62
	v_rcp_f32_e32 v63, v63
	v_pk_add_f32 v[60:61], v[0:1], v[60:61] op_sel:[1,0] op_sel_hi:[0,1]
	v_pk_fma_f32 v[62:63], v[62:63], 2.0, 1.0 op_sel_hi:[1,0,0] neg_lo:[1,0,0] neg_hi:[1,0,0]
	s_nop 0
	v_pk_add_f32 v[62:63], v[62:63], 1.0 op_sel_hi:[1,0]
	s_nop 0
	v_pk_mul_f32 v[62:63], v[38:39], v[62:63]
	s_nop 0
	v_pk_mul_f32 v[60:61], v[60:61], v[62:63]
	s_nop 0
	v_cvt_pk_bf16_f32 v60, v60, v61
	global_store_dword v[6:7], v60, off
	v_lshl_add_u64 v[6:7], v[6:7], 0, s[16:17]
	s_waitcnt vmcnt(45)
	v_and_b32_e32 v56, 0xffff0000, v44
	v_lshlrev_b32_e32 v57, 16, v44
	v_mul_f32_e32 v56, 0x3fb8aa3b, v56
	v_mul_f32_e32 v57, 0x3fb8aa3b, v57
	v_exp_f32_e32 v56, v56
	v_exp_f32_e32 v57, v57
	v_and_b32_e32 v58, 0xffff0000, v45
	v_lshlrev_b32_e32 v59, 16, v45
	v_lshlrev_b32_e32 v60, 16, v46
	v_and_b32_e32 v61, 0xffff0000, v46
	v_pk_fma_f32 v[0:1], v[0:1], v[56:57], v[58:59]
	v_mul_f32_e32 v62, 0x3d372713, v60
	v_mul_f32_e32 v63, 0x3d372713, v61
	v_pk_mul_f32 v[38:39], v[60:61], 0.5 op_sel_hi:[1,0]
	v_mul_f32_e32 v62, v62, v60
	v_mul_f32_e32 v63, v63, v61
	v_fma_f32 v62, v62, v60, v60
	v_fma_f32 v63, v63, v61, v61
	v_mul_f32_e32 v62, 0x3f4c422a, v62
	v_mul_f32_e32 v63, 0x3f4c422a, v63
	v_add_f32_e32 v62, v62, v62
	v_add_f32_e32 v63, v63, v63
	v_mul_f32_e32 v62, 0x3fb8aa3b, v62
	v_mul_f32_e32 v63, 0x3fb8aa3b, v63
	v_exp_f32_e32 v62, v62
	v_exp_f32_e32 v63, v63
	v_lshlrev_b32_e32 v60, 16, v47
	v_and_b32_e32 v61, 0xffff0000, v47
	v_add_f32_e32 v62, 1.0, v62
	v_add_f32_e32 v63, 1.0, v63
	v_rcp_f32_e32 v62, v62
	v_rcp_f32_e32 v63, v63
	v_pk_add_f32 v[60:61], v[0:1], v[60:61] op_sel:[1,0] op_sel_hi:[0,1]
	v_pk_fma_f32 v[62:63], v[62:63], 2.0, 1.0 op_sel_hi:[1,0,0] neg_lo:[1,0,0] neg_hi:[1,0,0]
	s_nop 0
	v_pk_add_f32 v[62:63], v[62:63], 1.0 op_sel_hi:[1,0]
	s_nop 0
	v_pk_mul_f32 v[62:63], v[38:39], v[62:63]
	s_nop 0
	v_pk_mul_f32 v[60:61], v[60:61], v[62:63]
	s_nop 0
	v_cvt_pk_bf16_f32 v60, v60, v61
	global_store_dword v[6:7], v60, off
	v_lshl_add_u64 v[6:7], v[6:7], 0, s[16:17]
	s_waitcnt vmcnt(42)
	v_and_b32_e32 v56, 0xffff0000, v48
	v_lshlrev_b32_e32 v57, 16, v48
	v_mul_f32_e32 v56, 0x3fb8aa3b, v56
	v_mul_f32_e32 v57, 0x3fb8aa3b, v57
	v_exp_f32_e32 v56, v56
	v_exp_f32_e32 v57, v57
	v_and_b32_e32 v58, 0xffff0000, v49
	v_lshlrev_b32_e32 v59, 16, v49
	v_lshlrev_b32_e32 v60, 16, v50
	v_and_b32_e32 v61, 0xffff0000, v50
	v_pk_fma_f32 v[0:1], v[0:1], v[56:57], v[58:59]
	v_mul_f32_e32 v62, 0x3d372713, v60
	v_mul_f32_e32 v63, 0x3d372713, v61
	v_pk_mul_f32 v[38:39], v[60:61], 0.5 op_sel_hi:[1,0]
	v_mul_f32_e32 v62, v62, v60
	v_mul_f32_e32 v63, v63, v61
	v_fma_f32 v62, v62, v60, v60
	v_fma_f32 v63, v63, v61, v61
	v_mul_f32_e32 v62, 0x3f4c422a, v62
	v_mul_f32_e32 v63, 0x3f4c422a, v63
	v_add_f32_e32 v62, v62, v62
	v_add_f32_e32 v63, v63, v63
	v_mul_f32_e32 v62, 0x3fb8aa3b, v62
	v_mul_f32_e32 v63, 0x3fb8aa3b, v63
	v_exp_f32_e32 v62, v62
	v_exp_f32_e32 v63, v63
	v_lshlrev_b32_e32 v60, 16, v51
	v_and_b32_e32 v61, 0xffff0000, v51
	v_add_f32_e32 v62, 1.0, v62
	v_add_f32_e32 v63, 1.0, v63
	v_rcp_f32_e32 v62, v62
	v_rcp_f32_e32 v63, v63
	v_pk_add_f32 v[60:61], v[0:1], v[60:61] op_sel:[1,0] op_sel_hi:[0,1]
	v_pk_fma_f32 v[62:63], v[62:63], 2.0, 1.0 op_sel_hi:[1,0,0] neg_lo:[1,0,0] neg_hi:[1,0,0]
	s_nop 0
	v_pk_add_f32 v[62:63], v[62:63], 1.0 op_sel_hi:[1,0]
	s_nop 0
	v_pk_mul_f32 v[62:63], v[38:39], v[62:63]
	s_nop 0
	v_pk_mul_f32 v[60:61], v[60:61], v[62:63]
	s_nop 0
	v_cvt_pk_bf16_f32 v60, v60, v61
	global_store_dword v[6:7], v60, off
	v_lshl_add_u64 v[6:7], v[6:7], 0, s[16:17]
	s_waitcnt vmcnt(39)
; __device__ __forceinline__ unsigned cvt_pk_bf16(float lo, float hi) { const f32x2_t v = {lo, hi}; const bf16x2_t b = __builtin_convertvector(v, bf16x2_t); return __builtin_bit_cast(unsigned, b); }
; __device__ __forceinline__ float lo_bf(unsigned w) { return __uint_as_float(w << 16); }
; __device__ __forceinline__ float hi_bf(unsigned w) { return __uint_as_float(w & 0xffff0000u); }
; __device__ __forceinline__ float gelu_tanh_(float gx) { const float inner = 0.7978845608028654f * (gx + 0.044715f * gx * gx * gx); const float th = 1.0f - 2.0f * __builtin_amdgcn_rcpf(1.0f + __expf(2.0f * inner)); return 0.5f * gx * (1.0f + th); }
; __device__ void rg_scan_phase(unsigned char* smem, const Params& p) {
;     ...
;         for (int i = 0; i < 128; ++i) { const int tt = 127 - i; const unsigned l1 = *(const unsigned*)(la1 + (size_t)tt * 512), v1 = *(const unsigned*)(u1 + (size_t)tt * 512);
;             hbx = __expf(lo_bf(l1)) * hbx + lo_bf(v1); hby = __expf(hi_bf(l1)) * hby + hi_bf(v1);
;             const unsigned gw = *(const unsigned*)(gp + (size_t)tt * 1024), hw = *(const unsigned*)(hfp + (size_t)tt * 512);
;             *(unsigned*)(yo + (size_t)tt * 1536) = cvt_pk_bf16((lo_bf(hw) + hbx) * gelu_tanh_(lo_bf(gw)), (hi_bf(hw) + hby) * gelu_tanh_(hi_bf(gw))); }
	v_and_b32_e32 v56, 0xffff0000, v52
	v_lshlrev_b32_e32 v57, 16, v52
	v_mul_f32_e32 v56, 0x3fb8aa3b, v56
	v_mul_f32_e32 v57, 0x3fb8aa3b, v57
	v_exp_f32_e32 v56, v56
	v_exp_f32_e32 v57, v57
	v_and_b32_e32 v58, 0xffff0000, v53
	v_lshlrev_b32_e32 v59, 16, v53
	v_lshlrev_b32_e32 v60, 16, v54
	v_and_b32_e32 v61, 0xffff0000, v54
	v_pk_fma_f32 v[0:1], v[0:1], v[56:57], v[58:59]
	v_mul_f32_e32 v62, 0x3d372713, v60
	v_mul_f32_e32 v63, 0x3d372713, v61
	v_pk_mul_f32 v[38:39], v[60:61], 0.5 op_sel_hi:[1,0]
	v_mul_f32_e32 v62, v62, v60
	v_mul_f32_e32 v63, v63, v61
	v_fma_f32 v62, v62, v60, v60
	v_fma_f32 v63, v63, v61, v61
	v_mul_f32_e32 v62, 0x3f4c422a, v62
	v_mul_f32_e32 v63, 0x3f4c422a, v63
	v_add_f32_e32 v62, v62, v62
	v_add_f32_e32 v63, v63, v63
	v_mul_f32_e32 v62, 0x3fb8aa3b, v62
	v_mul_f32_e32 v63, 0x3fb8aa3b, v63
	v_exp_f32_e32 v62, v62
	v_exp_f32_e32 v63, v63
	v_lshlrev_b32_e32 v60, 16, v55
	v_and_b32_e32 v61, 0xffff0000, v55
	v_add_f32_e32 v62, 1.0, v62
	v_add_f32_e32 v63, 1.0, v63
	v_rcp_f32_e32 v62, v62
	v_rcp_f32_e32 v63, v63
	v_pk_add_f32 v[60:61], v[0:1], v[60:61] op_sel:[1,0] op_sel_hi:[0,1]
	v_pk_fma_f32 v[62:63], v[62:63], 2.0, 1.0 op_sel_hi:[1,0,0] neg_lo:[1,0,0] neg_hi:[1,0,0]
	s_nop 0
	v_pk_add_f32 v[62:63], v[62:63], 1.0 op_sel_hi:[1,0]
	s_nop 0
	v_pk_mul_f32 v[62:63], v[38:39], v[62:63]
	s_nop 0
	v_pk_mul_f32 v[60:61], v[60:61], v[62:63]
	s_nop 0
	v_cvt_pk_bf16_f32 v60, v60, v61
	global_store_dword v[6:7], v60, off
	v_lshl_add_u64 v[6:7], v[6:7], 0, s[16:17]
	s_movk_i32 s0, 0xa000
	s_mov_b32 s1, -1
	v_lshl_add_u64 v[2:3], v[2:3], 0, s[0:1]
	s_add_i32 s12, s12, -8
	v_lshl_add_u64 v[90:91], s[6:7], 0, v[14:15]
	s_mov_b32 s0, 0x14c1fc00
	s_mov_b32 s1, 0
	v_lshl_add_u64 v[38:39], v[90:91], 0, s[0:1]
	s_mov_b32 s0, 0x18c1fc00
	v_lshl_add_u64 v[56:57], v[90:91], 0, s[0:1]
	s_mov_b32 s0, 0x1ac1fc00
	v_lshl_add_u64 v[58:59], v[90:91], 0, s[0:1]
	v_lshl_add_u64 v[60:61], s[6:7], 0, v[4:5]
	s_mov_b32 s0, 0xdc3fc00
	v_lshl_add_u64 v[60:61], v[60:61], 0, s[0:1]
	s_mov_b32 s14, 0xfffff000
	s_mov_b32 s15, -1
	global_load_dword v16, v[38:39], off
	global_load_dword v17, v[56:57], off
	global_load_dword v18, v[60:61], off
	global_load_dword v19, v[58:59], off
	global_load_dword v20, v[38:39], off offset:-1024
	global_load_dword v21, v[56:57], off offset:-1024
	global_load_dword v22, v[60:61], off offset:-2048
	global_load_dword v23, v[58:59], off offset:-1024
	v_lshl_add_u64 v[60:61], v[60:61], 0, s[14:15]
	global_load_dword v24, v[38:39], off offset:-2048
	global_load_dword v25, v[56:57], off offset:-2048
	global_load_dword v26, v[60:61], off
	global_load_dword v27, v[58:59], off offset:-2048
	global_load_dword v28, v[38:39], off offset:-3072
	global_load_dword v29, v[56:57], off offset:-3072
	global_load_dword v30, v[60:61], off offset:-2048
	global_load_dword v31, v[58:59], off offset:-3072
	v_lshl_add_u64 v[38:39], v[38:39], 0, s[14:15]
	v_lshl_add_u64 v[56:57], v[56:57], 0, s[14:15]
	v_lshl_add_u64 v[58:59], v[58:59], 0, s[14:15]
	v_lshl_add_u64 v[60:61], v[60:61], 0, s[14:15]
	global_load_dword v40, v[38:39], off
	global_load_dword v41, v[56:57], off
	global_load_dword v42, v[60:61], off
	global_load_dword v43, v[58:59], off
	global_load_dword v44, v[38:39], off offset:-1024
	global_load_dword v45, v[56:57], off offset:-1024
	global_load_dword v46, v[60:61], off offset:-2048
	global_load_dword v47, v[58:59], off offset:-1024
	v_lshl_add_u64 v[60:61], v[60:61], 0, s[14:15]
	global_load_dword v48, v[38:39], off offset:-2048
	global_load_dword v49, v[56:57], off offset:-2048
	global_load_dword v50, v[60:61], off
	global_load_dword v51, v[58:59], off offset:-2048
	global_load_dword v52, v[38:39], off offset:-3072
	global_load_dword v53, v[56:57], off offset:-3072
	global_load_dword v54, v[60:61], off offset:-2048
	global_load_dword v55, v[58:59], off offset:-3072
	v_lshl_add_u64 v[14:15], v[14:15], 0, s[36:37]
	s_movk_i32 s14, 0xc000
	v_lshl_add_u64 v[4:5], v[4:5], 0, s[14:15]
	v_lshl_add_u64 v[6:7], s[6:7], 0, v[2:3]
	s_mov_b32 s0, 0x1cc5fc00
	s_mov_b32 s1, 0
	v_lshl_add_u64 v[6:7], v[6:7], 0, s[0:1]
	s_mov_b32 s16, 0xfffff400
	s_mov_b32 s17, -1
	s_waitcnt vmcnt(60)
	v_and_b32_e32 v56, 0xffff0000, v96
	v_lshlrev_b32_e32 v57, 16, v96
	v_mul_f32_e32 v56, 0x3fb8aa3b, v56
	v_mul_f32_e32 v57, 0x3fb8aa3b, v57
	v_exp_f32_e32 v56, v56
	v_exp_f32_e32 v57, v57
	v_and_b32_e32 v58, 0xffff0000, v97
	v_lshlrev_b32_e32 v59, 16, v97
	v_lshlrev_b32_e32 v60, 16, v98
	v_and_b32_e32 v61, 0xffff0000, v98
	v_pk_fma_f32 v[0:1], v[0:1], v[56:57], v[58:59]
	v_mul_f32_e32 v62, 0x3d372713, v60
	v_mul_f32_e32 v63, 0x3d372713, v61
	v_pk_mul_f32 v[38:39], v[60:61], 0.5 op_sel_hi:[1,0]
	v_mul_f32_e32 v62, v62, v60
	v_mul_f32_e32 v63, v63, v61
	v_fma_f32 v62, v62, v60, v60
	v_fma_f32 v63, v63, v61, v61
	v_mul_f32_e32 v62, 0x3f4c422a, v62
	v_mul_f32_e32 v63, 0x3f4c422a, v63
	v_add_f32_e32 v62, v62, v62
	v_add_f32_e32 v63, v63, v63
	v_mul_f32_e32 v62, 0x3fb8aa3b, v62
	v_mul_f32_e32 v63, 0x3fb8aa3b, v63
	v_exp_f32_e32 v62, v62
	v_exp_f32_e32 v63, v63
	v_lshlrev_b32_e32 v60, 16, v99
	v_and_b32_e32 v61, 0xffff0000, v99
	v_add_f32_e32 v62, 1.0, v62
	v_add_f32_e32 v63, 1.0, v63
	v_rcp_f32_e32 v62, v62
	v_rcp_f32_e32 v63, v63
	v_pk_add_f32 v[60:61], v[0:1], v[60:61] op_sel:[1,0] op_sel_hi:[0,1]
	v_pk_fma_f32 v[62:63], v[62:63], 2.0, 1.0 op_sel_hi:[1,0,0] neg_lo:[1,0,0] neg_hi:[1,0,0]
	s_nop 0
	v_pk_add_f32 v[62:63], v[62:63], 1.0 op_sel_hi:[1,0]
	s_nop 0
	v_pk_mul_f32 v[62:63], v[38:39], v[62:63]
	s_nop 0
	v_pk_mul_f32 v[60:61], v[60:61], v[62:63]
	s_nop 0
	v_cvt_pk_bf16_f32 v60, v60, v61
	global_store_dword v[6:7], v60, off
	v_lshl_add_u64 v[6:7], v[6:7], 0, s[16:17]
	s_waitcnt vmcnt(57)
; __device__ __forceinline__ unsigned cvt_pk_bf16(float lo, float hi) { const f32x2_t v = {lo, hi}; const bf16x2_t b = __builtin_convertvector(v, bf16x2_t); return __builtin_bit_cast(unsigned, b); }
; __device__ __forceinline__ float lo_bf(unsigned w) { return __uint_as_float(w << 16); }
; __device__ __forceinline__ float hi_bf(unsigned w) { return __uint_as_float(w & 0xffff0000u); }
; __device__ __forceinline__ float gelu_tanh_(float gx) { const float inner = 0.7978845608028654f * (gx + 0.044715f * gx * gx * gx); const float th = 1.0f - 2.0f * __builtin_amdgcn_rcpf(1.0f + __expf(2.0f * inner)); return 0.5f * gx * (1.0f + th); }
; __device__ void rg_scan_phase(unsigned char* smem, const Params& p) {
;     ...
;         for (int i = 0; i < 128; ++i) { const int tt = 127 - i; const unsigned l1 = *(const unsigned*)(la1 + (size_t)tt * 512), v1 = *(const unsigned*)(u1 + (size_t)tt * 512);
;             hbx = __expf(lo_bf(l1)) * hbx + lo_bf(v1); hby = __expf(hi_bf(l1)) * hby + hi_bf(v1);
;             const unsigned gw = *(const unsigned*)(gp + (size_t)tt * 1024), hw = *(const unsigned*)(hfp + (size_t)tt * 512);
;             *(unsigned*)(yo + (size_t)tt * 1536) = cvt_pk_bf16((lo_bf(hw) + hbx) * gelu_tanh_(lo_bf(gw)), (hi_bf(hw) + hby) * gelu_tanh_(hi_bf(gw))); }
	v_and_b32_e32 v56, 0xffff0000, v100
	v_lshlrev_b32_e32 v57, 16, v100
	v_mul_f32_e32 v56, 0x3fb8aa3b, v56
	v_mul_f32_e32 v57, 0x3fb8aa3b, v57
	v_exp_f32_e32 v56, v56
	v_exp_f32_e32 v57, v57
	v_and_b32_e32 v58, 0xffff0000, v101
	v_lshlrev_b32_e32 v59, 16, v101
	v_lshlrev_b32_e32 v60, 16, v102
	v_and_b32_e32 v61, 0xffff0000, v102
	v_pk_fma_f32 v[0:1], v[0:1], v[56:57], v[58:59]
	v_mul_f32_e32 v62, 0x3d372713, v60
	v_mul_f32_e32 v63, 0x3d372713, v61
	v_pk_mul_f32 v[38:39], v[60:61], 0.5 op_sel_hi:[1,0]
	v_mul_f32_e32 v62, v62, v60
	v_mul_f32_e32 v63, v63, v61
	v_fma_f32 v62, v62, v60, v60
	v_fma_f32 v63, v63, v61, v61
	v_mul_f32_e32 v62, 0x3f4c422a, v62
	v_mul_f32_e32 v63, 0x3f4c422a, v63
	v_add_f32_e32 v62, v62, v62
	v_add_f32_e32 v63, v63, v63
	v_mul_f32_e32 v62, 0x3fb8aa3b, v62
	v_mul_f32_e32 v63, 0x3fb8aa3b, v63
	v_exp_f32_e32 v62, v62
	v_exp_f32_e32 v63, v63
	v_lshlrev_b32_e32 v60, 16, v103
	v_and_b32_e32 v61, 0xffff0000, v103
	v_add_f32_e32 v62, 1.0, v62
	v_add_f32_e32 v63, 1.0, v63
	v_rcp_f32_e32 v62, v62
	v_rcp_f32_e32 v63, v63
	v_pk_add_f32 v[60:61], v[0:1], v[60:61] op_sel:[1,0] op_sel_hi:[0,1]
	v_pk_fma_f32 v[62:63], v[62:63], 2.0, 1.0 op_sel_hi:[1,0,0] neg_lo:[1,0,0] neg_hi:[1,0,0]
	s_nop 0
	v_pk_add_f32 v[62:63], v[62:63], 1.0 op_sel_hi:[1,0]
	s_nop 0
	v_pk_mul_f32 v[62:63], v[38:39], v[62:63]
	s_nop 0
	v_pk_mul_f32 v[60:61], v[60:61], v[62:63]
	s_nop 0
	v_cvt_pk_bf16_f32 v60, v60, v61
	global_store_dword v[6:7], v60, off
	v_lshl_add_u64 v[6:7], v[6:7], 0, s[16:17]
	s_waitcnt vmcnt(54)
	v_and_b32_e32 v56, 0xffff0000, v104
	v_lshlrev_b32_e32 v57, 16, v104
	v_mul_f32_e32 v56, 0x3fb8aa3b, v56
	v_mul_f32_e32 v57, 0x3fb8aa3b, v57
	v_exp_f32_e32 v56, v56
	v_exp_f32_e32 v57, v57
	v_and_b32_e32 v58, 0xffff0000, v105
	v_lshlrev_b32_e32 v59, 16, v105
	v_lshlrev_b32_e32 v60, 16, v106
	v_and_b32_e32 v61, 0xffff0000, v106
	v_pk_fma_f32 v[0:1], v[0:1], v[56:57], v[58:59]
	v_mul_f32_e32 v62, 0x3d372713, v60
	v_mul_f32_e32 v63, 0x3d372713, v61
	v_pk_mul_f32 v[38:39], v[60:61], 0.5 op_sel_hi:[1,0]
	v_mul_f32_e32 v62, v62, v60
	v_mul_f32_e32 v63, v63, v61
	v_fma_f32 v62, v62, v60, v60
	v_fma_f32 v63, v63, v61, v61
	v_mul_f32_e32 v62, 0x3f4c422a, v62
	v_mul_f32_e32 v63, 0x3f4c422a, v63
	v_add_f32_e32 v62, v62, v62
	v_add_f32_e32 v63, v63, v63
	v_mul_f32_e32 v62, 0x3fb8aa3b, v62
	v_mul_f32_e32 v63, 0x3fb8aa3b, v63
	v_exp_f32_e32 v62, v62
	v_exp_f32_e32 v63, v63
	v_lshlrev_b32_e32 v60, 16, v107
	v_and_b32_e32 v61, 0xffff0000, v107
	v_add_f32_e32 v62, 1.0, v62
	v_add_f32_e32 v63, 1.0, v63
	v_rcp_f32_e32 v62, v62
	v_rcp_f32_e32 v63, v63
	v_pk_add_f32 v[60:61], v[0:1], v[60:61] op_sel:[1,0] op_sel_hi:[0,1]
	v_pk_fma_f32 v[62:63], v[62:63], 2.0, 1.0 op_sel_hi:[1,0,0] neg_lo:[1,0,0] neg_hi:[1,0,0]
	s_nop 0
	v_pk_add_f32 v[62:63], v[62:63], 1.0 op_sel_hi:[1,0]
	s_nop 0
	v_pk_mul_f32 v[62:63], v[38:39], v[62:63]
	s_nop 0
	v_pk_mul_f32 v[60:61], v[60:61], v[62:63]
	s_nop 0
	v_cvt_pk_bf16_f32 v60, v60, v61
	global_store_dword v[6:7], v60, off
	v_lshl_add_u64 v[6:7], v[6:7], 0, s[16:17]
	s_waitcnt vmcnt(51)
	v_and_b32_e32 v56, 0xffff0000, v108
	v_lshlrev_b32_e32 v57, 16, v108
	v_mul_f32_e32 v56, 0x3fb8aa3b, v56
	v_mul_f32_e32 v57, 0x3fb8aa3b, v57
	v_exp_f32_e32 v56, v56
	v_exp_f32_e32 v57, v57
	v_and_b32_e32 v58, 0xffff0000, v109
	v_lshlrev_b32_e32 v59, 16, v109
	v_lshlrev_b32_e32 v60, 16, v110
	v_and_b32_e32 v61, 0xffff0000, v110
	v_pk_fma_f32 v[0:1], v[0:1], v[56:57], v[58:59]
	v_mul_f32_e32 v62, 0x3d372713, v60
	v_mul_f32_e32 v63, 0x3d372713, v61
	v_pk_mul_f32 v[38:39], v[60:61], 0.5 op_sel_hi:[1,0]
	v_mul_f32_e32 v62, v62, v60
	v_mul_f32_e32 v63, v63, v61
	v_fma_f32 v62, v62, v60, v60
	v_fma_f32 v63, v63, v61, v61
	v_mul_f32_e32 v62, 0x3f4c422a, v62
	v_mul_f32_e32 v63, 0x3f4c422a, v63
	v_add_f32_e32 v62, v62, v62
	v_add_f32_e32 v63, v63, v63
	v_mul_f32_e32 v62, 0x3fb8aa3b, v62
	v_mul_f32_e32 v63, 0x3fb8aa3b, v63
	v_exp_f32_e32 v62, v62
	v_exp_f32_e32 v63, v63
	v_lshlrev_b32_e32 v60, 16, v111
	v_and_b32_e32 v61, 0xffff0000, v111
	v_add_f32_e32 v62, 1.0, v62
	v_add_f32_e32 v63, 1.0, v63
	v_rcp_f32_e32 v62, v62
	v_rcp_f32_e32 v63, v63
	v_pk_add_f32 v[60:61], v[0:1], v[60:61] op_sel:[1,0] op_sel_hi:[0,1]
	v_pk_fma_f32 v[62:63], v[62:63], 2.0, 1.0 op_sel_hi:[1,0,0] neg_lo:[1,0,0] neg_hi:[1,0,0]
	s_nop 0
	v_pk_add_f32 v[62:63], v[62:63], 1.0 op_sel_hi:[1,0]
	s_nop 0
	v_pk_mul_f32 v[62:63], v[38:39], v[62:63]
	s_nop 0
	v_pk_mul_f32 v[60:61], v[60:61], v[62:63]
	s_nop 0
	v_cvt_pk_bf16_f32 v60, v60, v61
	global_store_dword v[6:7], v60, off
	v_lshl_add_u64 v[6:7], v[6:7], 0, s[16:17]
	s_waitcnt vmcnt(48)
	v_and_b32_e32 v56, 0xffff0000, v112
	v_lshlrev_b32_e32 v57, 16, v112
	v_mul_f32_e32 v56, 0x3fb8aa3b, v56
	v_mul_f32_e32 v57, 0x3fb8aa3b, v57
	v_exp_f32_e32 v56, v56
	v_exp_f32_e32 v57, v57
	v_and_b32_e32 v58, 0xffff0000, v113
	v_lshlrev_b32_e32 v59, 16, v113
	v_lshlrev_b32_e32 v60, 16, v114
	v_and_b32_e32 v61, 0xffff0000, v114
	v_pk_fma_f32 v[0:1], v[0:1], v[56:57], v[58:59]
	v_mul_f32_e32 v62, 0x3d372713, v60
	v_mul_f32_e32 v63, 0x3d372713, v61
	v_pk_mul_f32 v[38:39], v[60:61], 0.5 op_sel_hi:[1,0]
	v_mul_f32_e32 v62, v62, v60
	v_mul_f32_e32 v63, v63, v61
	v_fma_f32 v62, v62, v60, v60
	v_fma_f32 v63, v63, v61, v61
	v_mul_f32_e32 v62, 0x3f4c422a, v62
	v_mul_f32_e32 v63, 0x3f4c422a, v63
	v_add_f32_e32 v62, v62, v62
	v_add_f32_e32 v63, v63, v63
	v_mul_f32_e32 v62, 0x3fb8aa3b, v62
	v_mul_f32_e32 v63, 0x3fb8aa3b, v63
	v_exp_f32_e32 v62, v62
	v_exp_f32_e32 v63, v63
	v_lshlrev_b32_e32 v60, 16, v115
	v_and_b32_e32 v61, 0xffff0000, v115
	v_add_f32_e32 v62, 1.0, v62
	v_add_f32_e32 v63, 1.0, v63
	v_rcp_f32_e32 v62, v62
	v_rcp_f32_e32 v63, v63
	v_pk_add_f32 v[60:61], v[0:1], v[60:61] op_sel:[1,0] op_sel_hi:[0,1]
	v_pk_fma_f32 v[62:63], v[62:63], 2.0, 1.0 op_sel_hi:[1,0,0] neg_lo:[1,0,0] neg_hi:[1,0,0]
	s_nop 0
	v_pk_add_f32 v[62:63], v[62:63], 1.0 op_sel_hi:[1,0]
	s_nop 0
	v_pk_mul_f32 v[62:63], v[38:39], v[62:63]
	s_nop 0
	v_pk_mul_f32 v[60:61], v[60:61], v[62:63]
	s_nop 0
	v_cvt_pk_bf16_f32 v60, v60, v61
	global_store_dword v[6:7], v60, off
	v_lshl_add_u64 v[6:7], v[6:7], 0, s[16:17]
	s_waitcnt vmcnt(45)
; __device__ __forceinline__ unsigned cvt_pk_bf16(float lo, float hi) { const f32x2_t v = {lo, hi}; const bf16x2_t b = __builtin_convertvector(v, bf16x2_t); return __builtin_bit_cast(unsigned, b); }
; __device__ __forceinline__ float lo_bf(unsigned w) { return __uint_as_float(w << 16); }
; __device__ __forceinline__ float hi_bf(unsigned w) { return __uint_as_float(w & 0xffff0000u); }
; __device__ __forceinline__ float gelu_tanh_(float gx) { const float inner = 0.7978845608028654f * (gx + 0.044715f * gx * gx * gx); const float th = 1.0f - 2.0f * __builtin_amdgcn_rcpf(1.0f + __expf(2.0f * inner)); return 0.5f * gx * (1.0f + th); }
; __device__ void rg_scan_phase(unsigned char* smem, const Params& p) {
;     ...
;     for (int tile = blockIdx.x; tile < NB * 8; tile += gridDim.x) {
;     ...
;         for (int i = 0; i < 128; ++i) { const int tt = 127 - i; const unsigned l1 = *(const unsigned*)(la1 + (size_t)tt * 512), v1 = *(const unsigned*)(u1 + (size_t)tt * 512);
;             hbx = __expf(lo_bf(l1)) * hbx + lo_bf(v1); hby = __expf(hi_bf(l1)) * hby + hi_bf(v1);
;             const unsigned gw = *(const unsigned*)(gp + (size_t)tt * 1024), hw = *(const unsigned*)(hfp + (size_t)tt * 512);
;             *(unsigned*)(yo + (size_t)tt * 1536) = cvt_pk_bf16((lo_bf(hw) + hbx) * gelu_tanh_(lo_bf(gw)), (hi_bf(hw) + hby) * gelu_tanh_(hi_bf(gw))); }
	v_and_b32_e32 v56, 0xffff0000, v116
	v_lshlrev_b32_e32 v57, 16, v116
	v_mul_f32_e32 v56, 0x3fb8aa3b, v56
	v_mul_f32_e32 v57, 0x3fb8aa3b, v57
	v_exp_f32_e32 v56, v56
	v_exp_f32_e32 v57, v57
	v_and_b32_e32 v58, 0xffff0000, v117
	v_lshlrev_b32_e32 v59, 16, v117
	v_lshlrev_b32_e32 v60, 16, v118
	v_and_b32_e32 v61, 0xffff0000, v118
	v_pk_fma_f32 v[0:1], v[0:1], v[56:57], v[58:59]
	v_mul_f32_e32 v62, 0x3d372713, v60
	v_mul_f32_e32 v63, 0x3d372713, v61
	v_pk_mul_f32 v[38:39], v[60:61], 0.5 op_sel_hi:[1,0]
	v_mul_f32_e32 v62, v62, v60
	v_mul_f32_e32 v63, v63, v61
	v_fma_f32 v62, v62, v60, v60
	v_fma_f32 v63, v63, v61, v61
	v_mul_f32_e32 v62, 0x3f4c422a, v62
	v_mul_f32_e32 v63, 0x3f4c422a, v63
	v_add_f32_e32 v62, v62, v62
	v_add_f32_e32 v63, v63, v63
	v_mul_f32_e32 v62, 0x3fb8aa3b, v62
	v_mul_f32_e32 v63, 0x3fb8aa3b, v63
	v_exp_f32_e32 v62, v62
	v_exp_f32_e32 v63, v63
	v_lshlrev_b32_e32 v60, 16, v119
	v_and_b32_e32 v61, 0xffff0000, v119
	v_add_f32_e32 v62, 1.0, v62
	v_add_f32_e32 v63, 1.0, v63
	v_rcp_f32_e32 v62, v62
	v_rcp_f32_e32 v63, v63
	v_pk_add_f32 v[60:61], v[0:1], v[60:61] op_sel:[1,0] op_sel_hi:[0,1]
	v_pk_fma_f32 v[62:63], v[62:63], 2.0, 1.0 op_sel_hi:[1,0,0] neg_lo:[1,0,0] neg_hi:[1,0,0]
	s_nop 0
	v_pk_add_f32 v[62:63], v[62:63], 1.0 op_sel_hi:[1,0]
	s_nop 0
	v_pk_mul_f32 v[62:63], v[38:39], v[62:63]
	s_nop 0
	v_pk_mul_f32 v[60:61], v[60:61], v[62:63]
	s_nop 0
	v_cvt_pk_bf16_f32 v60, v60, v61
	global_store_dword v[6:7], v60, off
	v_lshl_add_u64 v[6:7], v[6:7], 0, s[16:17]
	s_waitcnt vmcnt(42)
	v_and_b32_e32 v56, 0xffff0000, v120
	v_lshlrev_b32_e32 v57, 16, v120
	v_mul_f32_e32 v56, 0x3fb8aa3b, v56
	v_mul_f32_e32 v57, 0x3fb8aa3b, v57
	v_exp_f32_e32 v56, v56
	v_exp_f32_e32 v57, v57
	v_and_b32_e32 v58, 0xffff0000, v121
	v_lshlrev_b32_e32 v59, 16, v121
	v_lshlrev_b32_e32 v60, 16, v122
	v_and_b32_e32 v61, 0xffff0000, v122
	v_pk_fma_f32 v[0:1], v[0:1], v[56:57], v[58:59]
	v_mul_f32_e32 v62, 0x3d372713, v60
	v_mul_f32_e32 v63, 0x3d372713, v61
	v_pk_mul_f32 v[38:39], v[60:61], 0.5 op_sel_hi:[1,0]
	v_mul_f32_e32 v62, v62, v60
	v_mul_f32_e32 v63, v63, v61
	v_fma_f32 v62, v62, v60, v60
	v_fma_f32 v63, v63, v61, v61
	v_mul_f32_e32 v62, 0x3f4c422a, v62
	v_mul_f32_e32 v63, 0x3f4c422a, v63
	v_add_f32_e32 v62, v62, v62
	v_add_f32_e32 v63, v63, v63
	v_mul_f32_e32 v62, 0x3fb8aa3b, v62
	v_mul_f32_e32 v63, 0x3fb8aa3b, v63
	v_exp_f32_e32 v62, v62
	v_exp_f32_e32 v63, v63
	v_lshlrev_b32_e32 v60, 16, v123
	v_and_b32_e32 v61, 0xffff0000, v123
	v_add_f32_e32 v62, 1.0, v62
	v_add_f32_e32 v63, 1.0, v63
	v_rcp_f32_e32 v62, v62
	v_rcp_f32_e32 v63, v63
	v_pk_add_f32 v[60:61], v[0:1], v[60:61] op_sel:[1,0] op_sel_hi:[0,1]
	v_pk_fma_f32 v[62:63], v[62:63], 2.0, 1.0 op_sel_hi:[1,0,0] neg_lo:[1,0,0] neg_hi:[1,0,0]
	s_nop 0
	v_pk_add_f32 v[62:63], v[62:63], 1.0 op_sel_hi:[1,0]
	s_nop 0
	v_pk_mul_f32 v[62:63], v[38:39], v[62:63]
	s_nop 0
	v_pk_mul_f32 v[60:61], v[60:61], v[62:63]
	s_nop 0
	v_cvt_pk_bf16_f32 v60, v60, v61
	global_store_dword v[6:7], v60, off
	v_lshl_add_u64 v[6:7], v[6:7], 0, s[16:17]
	s_waitcnt vmcnt(39)
	v_and_b32_e32 v56, 0xffff0000, v124
	v_lshlrev_b32_e32 v57, 16, v124
	v_mul_f32_e32 v56, 0x3fb8aa3b, v56
	v_mul_f32_e32 v57, 0x3fb8aa3b, v57
	v_exp_f32_e32 v56, v56
	v_exp_f32_e32 v57, v57
	v_and_b32_e32 v58, 0xffff0000, v125
	v_lshlrev_b32_e32 v59, 16, v125
	v_lshlrev_b32_e32 v60, 16, v126
	v_and_b32_e32 v61, 0xffff0000, v126
	v_pk_fma_f32 v[0:1], v[0:1], v[56:57], v[58:59]
	v_mul_f32_e32 v62, 0x3d372713, v60
	v_mul_f32_e32 v63, 0x3d372713, v61
	v_pk_mul_f32 v[38:39], v[60:61], 0.5 op_sel_hi:[1,0]
	v_mul_f32_e32 v62, v62, v60
	v_mul_f32_e32 v63, v63, v61
	v_fma_f32 v62, v62, v60, v60
	v_fma_f32 v63, v63, v61, v61
	v_mul_f32_e32 v62, 0x3f4c422a, v62
	v_mul_f32_e32 v63, 0x3f4c422a, v63
	v_add_f32_e32 v62, v62, v62
	v_add_f32_e32 v63, v63, v63
	v_mul_f32_e32 v62, 0x3fb8aa3b, v62
	v_mul_f32_e32 v63, 0x3fb8aa3b, v63
	v_exp_f32_e32 v62, v62
	v_exp_f32_e32 v63, v63
	v_lshlrev_b32_e32 v60, 16, v127
	v_and_b32_e32 v61, 0xffff0000, v127
	v_add_f32_e32 v62, 1.0, v62
	v_add_f32_e32 v63, 1.0, v63
	v_rcp_f32_e32 v62, v62
	v_rcp_f32_e32 v63, v63
	v_pk_add_f32 v[60:61], v[0:1], v[60:61] op_sel:[1,0] op_sel_hi:[0,1]
	v_pk_fma_f32 v[62:63], v[62:63], 2.0, 1.0 op_sel_hi:[1,0,0] neg_lo:[1,0,0] neg_hi:[1,0,0]
	s_nop 0
	v_pk_add_f32 v[62:63], v[62:63], 1.0 op_sel_hi:[1,0]
	s_nop 0
	v_pk_mul_f32 v[62:63], v[38:39], v[62:63]
	s_nop 0
	v_pk_mul_f32 v[60:61], v[60:61], v[62:63]
	s_nop 0
	v_cvt_pk_bf16_f32 v60, v60, v61
	global_store_dword v[6:7], v60, off
	v_lshl_add_u64 v[6:7], v[6:7], 0, s[16:17]
	s_movk_i32 s0, 0xa000
	s_mov_b32 s1, -1
	v_lshl_add_u64 v[2:3], v[2:3], 0, s[0:1]
	s_add_i32 s12, s12, -8
	s_cmp_eq_u32 s12, 0
	s_cbranch_scc0 .LBB0_181
	s_waitcnt vmcnt(0)
	s_add_i32 s22, s22, s5
	s_add_i32 s21, s21, s20
	s_cmpk_gt_i32 s22, 0x7f
	s_cbranch_scc0 .LBB0_168
